# attention phase: static priority raise for waves 4-7 (partner stagger)
# speedup vs baseline: 1.0147x; 1.0147x over previous
.LBB0_898:
	s_or_b64 exec, exec, s[6:7]
	s_waitcnt lgkmcnt(0)
	v_mov_b32_e32 v0, v242
	s_cmpk_gt_i32 s2, 0x2ff
	s_mov_b64 s[86:87], -1
	s_barrier
	s_cbranch_scc1 .LBB0_984
	v_readfirstlane_b32 s98, v242
	s_cmpk_lt_u32 s98, 0x100
	s_cbranch_scc1 .Lattn_prio_done
	s_setprio 1
.Lattn_prio_done:
	s_load_dwordx2 s[62:63], s[0:1], 0xd0
	v_ashrrev_i32_e32 v218, 4, v0
	v_and_b32_e32 v0, 15, v0
	v_lshlrev_b32_e32 v7, 4, v0
	v_ashrrev_i32_e32 v12, 2, v243
	s_waitcnt lgkmcnt(0)
	s_add_u32 s4, s62, 0x8000000
	s_addc_u32 s5, s63, 0
	s_add_u32 s8, s62, 0xe000000
	s_addc_u32 s9, s63, 0
	s_add_i32 s12, 0, 0x11800
	v_and_b32_e32 v162, -8, v12
	v_add_u32_e32 v12, s12, v7
	s_add_i32 s12, 0, 0x15c00
	v_add_u32_e32 v13, s12, v7
	s_movk_i32 s12, 0x110
	v_and_b32_e32 v5, 15, v243
	s_and_b32 s15, s97, 32
	v_mul_lo_u32 v221, v218, s12
	s_add_i32 s12, 0, 0x1a400
	v_or_b32_e32 v219, s15, v5
	v_add_u32_e32 v14, s12, v7
	s_add_i32 s12, 0, 0x1e800
	v_and_b32_e32 v8, -16, v243
	v_add_u32_e32 v15, s12, v7
	v_add_u32_e32 v223, 0, v7
	v_mul_u32_u24_e32 v7, 0x110, v219
	s_add_i32 s13, s15, 32
	v_add3_u32 v224, 0, v7, v8
	v_and_or_b32 v7, s13, 32, v5
	v_mul_u32_u24_e32 v7, 0x110, v7
	s_add_i32 s14, s15, 48
	v_add3_u32 v225, 0, v7, v8
	v_and_or_b32 v7, s14, 48, v5
	v_mul_u32_u24_e32 v7, 0x110, v7
	s_add_i32 s16, s15, 0x60
	v_add3_u32 v226, 0, v7, v8
	v_and_or_b32 v7, s16, 32, v5
	s_bfe_u32 s11, s78, 0x10006
	s_lshr_b32 s12, s13, 6
	s_lshr_b32 s13, s14, 6
	s_lshr_b32 s14, s16, 6
	v_mul_u32_u24_e32 v7, 0x110, v7
	s_add_i32 s16, s15, 0x70
	v_add3_u32 v227, 0, v7, v8
	s_lshr_b32 s15, s16, 6
	v_and_or_b32 v7, s16, 48, v5
	s_add_i32 s16, s11, 3
	s_lshl_b32 s17, s16, 5
	s_lshr_b32 s10, s78, 7
	s_lshl_b32 s19, s11, 5
	s_lshr_b32 s16, s16, 1
	s_and_b32 s17, s17, 32
	s_add_u32 s66, s54, 0x200
	s_addc_u32 s67, s55, 0
	s_add_u32 s68, s54, 0x1000
	s_addc_u32 s69, s55, 0
	s_add_u32 s70, s54, 0x1100
	v_ashrrev_i32_e32 v1, 4, v243
	s_addc_u32 s71, s55, 0
	v_lshlrev_b32_e32 v160, 2, v1
	v_bfe_u32 v9, v243, 2, 2
	s_add_u32 s72, s54, 0x1200
	v_or_b32_e32 v10, v160, v9
	v_mul_u32_u24_e32 v7, 0x110, v7
	s_addc_u32 s73, s55, 0
	v_add3_u32 v228, 0, v7, v8
	v_add_u32_e32 v7, s19, v10
	v_xad_u32 v8, s19, 32, v10
	v_add_u32_e32 v10, s17, v10
	s_mul_i32 s17, s53, s52
	s_add_u32 s74, s54, 0x1300
	s_mul_i32 s17, s17, s75
	s_addc_u32 s75, s55, 0
	v_writelane_b32 v255, s76, 4
	s_cmp_eq_u32 s3, 15
	s_cselect_b64 s[20:21], -1, 0
	v_writelane_b32 v255, s77, 5
	v_writelane_b32 v255, s20, 2
	s_cmp_eq_u32 s3, 14
	v_and_b32_e32 v6, 3, v243
	v_writelane_b32 v255, s21, 3
	s_cselect_b64 s[20:21], -1, 0
	v_writelane_b32 v255, s20, 6
	s_cmp_eq_u32 s3, 13
	s_movk_i32 s18, 0x120
	v_writelane_b32 v255, s21, 7
	s_cselect_b64 s[20:21], -1, 0
	v_writelane_b32 v255, s20, 8
	s_cmp_eq_u32 s3, 12
	v_lshlrev_b32_e32 v11, 3, v6
	v_writelane_b32 v255, s21, 9
	s_cselect_b64 s[20:21], -1, 0
	v_writelane_b32 v255, s20, 10
	s_cmp_eq_u32 s3, 11
	v_mul_lo_u32 v7, v7, s18
	v_writelane_b32 v255, s21, 11
	s_cselect_b64 s[20:21], -1, 0
	v_writelane_b32 v255, s20, 12
	s_cmp_eq_u32 s3, 10
	v_add_u32_e32 v232, s19, v160
	v_writelane_b32 v255, s21, 13
	s_cselect_b64 s[20:21], -1, 0
	v_writelane_b32 v255, s20, 14
	s_cmp_eq_u32 s3, 9
	v_lshlrev_b32_e32 v4, 3, v0
	v_writelane_b32 v255, s21, 15
	s_cselect_b64 s[20:21], -1, 0
	v_writelane_b32 v255, s20, 16
	s_cmp_eq_u32 s3, 8
	v_mov_b32_e32 v0, 0x3f80
	v_writelane_b32 v255, s21, 17
	s_cselect_b64 s[20:21], -1, 0
	v_writelane_b32 v255, s20, 18
	s_cmp_eq_u32 s3, 7
	v_cmp_eq_u32_e32 vcc, 0, v6
	v_writelane_b32 v255, s21, 19
	s_cselect_b64 s[20:21], -1, 0
	v_writelane_b32 v255, s20, 20
	s_cmp_eq_u32 s3, 6
	v_add3_u32 v229, 0, v7, v11
	v_writelane_b32 v255, s21, 21
	s_cselect_b64 s[20:21], -1, 0
	v_writelane_b32 v255, s20, 22
	s_cmp_eq_u32 s3, 5
	v_or_b32_e32 v7, v232, v9
	v_writelane_b32 v255, s21, 23
	s_cselect_b64 s[20:21], -1, 0
	s_cmp_eq_u32 s3, 4
	s_cselect_b64 s[30:31], -1, 0
	s_cmp_eq_u32 s3, 3
	s_cselect_b64 s[34:35], -1, 0
	s_cmp_eq_u32 s3, 2
	s_cselect_b64 s[36:37], -1, 0
	s_cmp_eq_u32 s3, 1
	v_writelane_b32 v255, s20, 24
	s_cselect_b64 s[38:39], -1, 0
	s_cmp_eq_u32 s3, 0
	v_writelane_b32 v255, s21, 25
	s_cselect_b64 s[40:41], -1, 0
	s_lshl_b32 s20, s3, 8
	s_add_u32 s20, s54, s20
	s_addc_u32 s21, s55, 0
	s_add_u32 s76, s20, 0x1400
	s_addc_u32 s77, s21, 0
	s_add_u32 s78, s20, 0x2400
	s_addc_u32 s79, s21, 0
	s_add_u32 s100, s54, 0x3500
	s_addc_u32 s101, s55, 0
	s_add_u32 s80, s54, 0x3400
	v_cndmask_b32_e32 v0, 0, v0, vcc
	s_mov_b32 s6, 0x5040100
	s_addc_u32 s81, s55, 0
	v_mul_lo_u32 v7, v7, s18
	v_lshlrev_b32_e32 v158, 3, v1
	v_perm_b32 v0, v0, v0, s6
	v_and_b32_e32 v6, 16, v243
	v_mul_lo_u32 v222, v218, s18
	v_mul_lo_u32 v8, v8, s18
	v_mul_lo_u32 v10, v10, s18
	s_add_u32 s82, s54, 0x3500
	v_or_b32_e32 v7, v7, v11
	v_or_b32_e32 v234, s19, v5
	s_mov_b32 s65, 0
	v_mov_b32_e32 v157, 0
	v_ashrrev_i32_e32 v159, 31, v158
	v_sub_u32_e32 v220, v5, v160
	v_mov_b32_e32 v1, v0
	v_mov_b32_e32 v2, v0
	v_mov_b32_e32 v3, v0
	v_ashrrev_i32_e32 v161, 31, v160
	v_ashrrev_i32_e32 v163, 31, v162
	v_cmp_gt_u32_e64 s[6:7], 16, v243
	s_addc_u32 s83, s55, 0
	v_add3_u32 v230, 0, v8, v11
	v_add3_u32 v231, 0, v10, v11
	v_add_u32_e32 v233, 0, v7
	v_or_b32_e32 v235, 0x50, v234
	v_add_u32_e32 v254, 0x60, v218
	v_or_b32_e32 v238, 16, v234
	s_mov_b64 s[84:85], 0
	s_add_i32 s18, 0, 0x243c0
	s_add_i32 s19, 0, 0x243c4
	v_mov_b32_e32 v239, 0xc2000
	s_movk_i32 s20, 0x1800
	v_lshlrev_b32_e32 v164, 1, v4
	s_movk_i32 s21, 0xc00
	v_add_u32_e32 v240, v12, v221
	v_add_u32_e32 v241, v13, v222
	v_add_u32_e32 v243, v14, v221
	v_add_u32_e32 v244, v15, v222
	v_lshlrev_b32_e32 v166, 1, v6
	s_mov_b32 s22, 0x3f317218
	v_mov_b32_e32 v245, 0xff61b1e6
	s_branch .LBB0_901

.LBB0_984:
	s_setprio 0
	s_and_b64 vcc, exec, s[86:87]
	s_cbranch_vccz .LBB0_1038
	s_waitcnt vmcnt(0)
	s_waitcnt lgkmcnt(0)
	s_barrier
	s_and_saveexec_b64 s[6:7], s[44:45]
	s_cbranch_execz .LBB0_1037
	s_add_i32 s2, 0, 0x243c0
	v_mov_b32_e32 v0, s2
	s_waitcnt vmcnt(0) expcnt(0) lgkmcnt(0)
	ds_read_b32 v2, v0
	s_add_i32 s2, 0, 0x243c4
	v_mov_b32_e32 v0, s2
	ds_read_b32 v0, v0
	s_waitcnt lgkmcnt(1)
	v_cmp_ne_u32_e32 vcc, 0, v2
	s_cbranch_vccnz .LBB0_1001
	s_add_u32 s8, s54, 0x1000
	s_addc_u32 s9, s55, 0
	s_add_u32 s10, s54, 0x1100
	s_addc_u32 s11, s55, 0
	s_add_u32 s12, s54, 0x1200
	s_addc_u32 s13, s55, 0
	s_mul_i32 s2, s53, s75
	s_add_u32 s14, s54, 0x1300
	s_mul_i32 s2, s2, s52
	s_addc_u32 s15, s55, 0
	s_mov_b32 s4, 1
	v_mov_b32_e32 v16, 0
	s_branch .LBB0_989
